# attention item epilogue: sink-parameter pointer/value and ws pointer preloaded in the item prologue (removes two serialized load-wait chains per item)
# baseline (speedup 1.0000x reference)
; __device__ __forceinline__ unsigned pack2(float a, float b) { unsigned r; asm("v_cvt_pk_bf16_f32 %0, %1, %2" : "=v"(r) : "v"(a), "v"(b)); return r; }
; #define layer launder_s(layer_)
; __device__ __forceinline__ void attn_item(const Params& p, int layer, bool isctx, int item, unsigned char* smem) {
;     ...
;   rsum += __shfl_xor(rsum, 32);
;   float denom = rsum + expf(p.in[21][layer * 8 + hq]);
;   float rinv = 1.0f / denom;
;   u16* YS = (u16*)(p.ws + O_YS) + (size_t)(qrow0 + ql) * 1536 + 512 + hq * 64;
; #pragma unroll
;   for (int mt = 0; mt < 2; mt++)
; #pragma unroll
;     for (int rq = 0; rq < 4; rq++) {
;       int d = mt * 32 + 8 * rq + 4 * hh;
;       uint2 o;
;       o.x = pack2(oacc[mt][rq * 4 + 0] * rinv, oacc[mt][rq * 4 + 1] * rinv);
;       o.y = pack2(oacc[mt][rq * 4 + 2] * rinv, oacc[mt][rq * 4 + 3] * rinv);
;       *(uint2*)(YS + d) = o;
;     }
;   __syncthreads();
.LBB0_482:
	v_mov_b32_e32 v32, v102
	v_mov_b32_e32 v33, v103
	v_cmp_lt_i32_e32 vcc, v236, v235
	v_readlane_b32 s6, v254, 42
	v_readlane_b32 s7, v254, 43
	s_add_i32 s5, s5, s6
	s_add_i32 s4, s4, s6
	v_lshlrev_b32_e32 v160, 1, v67
	s_cmpk_gt_i32 s5, 0x1ff
	s_waitcnt vmcnt(0) lgkmcnt(0)
	v_mov_b32_e32 v36, v106
	v_cndmask_b32_e32 v34, v234, v236, vcc
	v_lshlrev_b32_e32 v34, 2, v34
	ds_bpermute_b32 v34, v34, v86
	v_mad_i64_i32 v[32:33], s[6:7], v66, s69, v[32:33]
	v_lshl_add_u64 v[32:33], v[64:65], 1, v[32:33]
	v_lshl_add_u64 v[32:33], v[32:33], 0, v[160:161]
	s_waitcnt lgkmcnt(0)
	v_add_f32_e32 v37, v86, v34
	s_mov_b64 s[6:7], 0x1700c400
	s_waitcnt vmcnt(0)
	v_mul_f32_e32 v34, 0x3fb8aa3b, v36
	v_fma_f32 v35, v36, s55, -v34
	v_rndne_f32_e32 v38, v34
	v_fmac_f32_e32 v35, 0x32a5705f, v36
	v_sub_f32_e32 v34, v34, v38
	v_add_f32_e32 v34, v34, v35
	v_cvt_i32_f32_e32 v38, v38
	v_exp_f32_e32 v39, v34
	v_cmp_ngt_f32_e32 vcc, s56, v36
	v_lshl_add_u64 v[34:35], v[32:33], 0, s[6:7]
	v_ldexp_f32 v38, v39, v38
	v_cndmask_b32_e32 v38, 0, v38, vcc
	v_cmp_nlt_f32_e32 vcc, s54, v36
	s_nop 1
	v_cndmask_b32_e32 v36, v242, v38, vcc
	v_add_f32_e32 v36, v37, v36
	v_div_scale_f32 v37, s[6:7], v36, v36, 1.0
	v_rcp_f32_e32 v38, v37
	v_add_co_u32_e32 v32, vcc, s78, v32
	v_fma_f32 v40, -v37, v38, 1.0
	s_nop 0
	v_addc_co_u32_e32 v33, vcc, 0, v33, vcc
	v_div_scale_f32 v39, vcc, 1.0, v36, 1.0
	v_fmac_f32_e32 v38, v40, v38
	v_mul_f32_e32 v40, v39, v38
	v_fma_f32 v41, -v37, v40, v39
	v_fmac_f32_e32 v40, v41, v38
	v_fma_f32 v37, -v37, v40, v39
	v_div_fmas_f32 v37, v37, v38, v40
	v_div_fixup_f32 v36, v37, v36, 1.0
	v_mul_f32_e32 v16, v16, v36
	v_mul_f32_e32 v17, v17, v36
	v_mul_f32_e32 v18, v18, v36
	v_mul_f32_e32 v19, v19, v36
	v_mul_f32_e32 v37, v0, v36
	v_mul_f32_e32 v38, v1, v36
	v_mul_f32_e32 v15, v15, v36
	v_cvt_pk_bf16_f32 v0, v16, v17
	v_cvt_pk_bf16_f32 v1, v18, v19
	v_mul_f32_e32 v20, v20, v36
	v_mul_f32_e32 v21, v21, v36
	v_mul_f32_e32 v22, v22, v36
	v_mul_f32_e32 v23, v23, v36
	v_mul_f32_e32 v24, v24, v36
	v_mul_f32_e32 v25, v25, v36
	v_mul_f32_e32 v26, v26, v36
	v_mul_f32_e32 v27, v27, v36
	v_mul_f32_e32 v28, v28, v36
	v_mul_f32_e32 v29, v29, v36
	v_mul_f32_e32 v30, v30, v36
	v_mul_f32_e32 v31, v31, v36
	v_mul_f32_e32 v39, v2, v36
	v_mul_f32_e32 v40, v3, v36
	v_mul_f32_e32 v41, v4, v36
	v_mul_f32_e32 v42, v5, v36
	v_mul_f32_e32 v43, v6, v36
	v_mul_f32_e32 v44, v7, v36
	v_mul_f32_e32 v45, v8, v36
	v_mul_f32_e32 v46, v9, v36
	v_mul_f32_e32 v47, v10, v36
	v_mul_f32_e32 v48, v11, v36
	v_mul_f32_e32 v49, v12, v36
	v_mul_f32_e32 v50, v13, v36
	v_mul_f32_e32 v51, v14, v36
	v_cvt_pk_bf16_f32 v2, v20, v21
	v_cvt_pk_bf16_f32 v3, v22, v23
	v_cvt_pk_bf16_f32 v4, v24, v25
	v_cvt_pk_bf16_f32 v5, v26, v27
	v_cvt_pk_bf16_f32 v6, v28, v29
	v_cvt_pk_bf16_f32 v7, v30, v31
	v_cvt_pk_bf16_f32 v8, v37, v38
	v_cvt_pk_bf16_f32 v9, v39, v40
	v_cvt_pk_bf16_f32 v10, v41, v42
	v_cvt_pk_bf16_f32 v11, v43, v44
	v_cvt_pk_bf16_f32 v12, v45, v46
	v_cvt_pk_bf16_f32 v13, v47, v48
	v_cvt_pk_bf16_f32 v14, v49, v50
	v_cvt_pk_bf16_f32 v15, v51, v15
	global_store_dwordx2 v[32:33], v[0:1], off offset:1024
	global_store_dwordx2 v[34:35], v[2:3], off offset:16
	global_store_dwordx2 v[34:35], v[4:5], off offset:32
	global_store_dwordx2 v[34:35], v[6:7], off offset:48
	global_store_dwordx2 v[34:35], v[8:9], off offset:64
	global_store_dwordx2 v[34:35], v[10:11], off offset:80
	global_store_dwordx2 v[34:35], v[12:13], off offset:96
	global_store_dwordx2 v[34:35], v[14:15], off offset:112
	s_waitcnt lgkmcnt(0)
	s_barrier
	s_cbranch_scc1 .LBB0_473
; __device__ __forceinline__ int opaque_tid() { int t = threadIdx.x; asm volatile("" : "+v"(t)); return t; }
; #define layer launder_s(layer_)
; __device__ __forceinline__ void attn_item(const Params& p, int layer, bool isctx, int item, unsigned char* smem) {
;   u16* Ks = (u16*)smem;
;   u16* Vt = Ks + 128 * 72;
;   int tid = opaque_tid(), wave = tid >> 6, lane = tid & 63;
;   int n, hq, b;
;   if (!isctx) { n = item & 15; hq = ((item >> 4) & 3) * 2 + (wave >> 2); b = item >> 6; }
;   else { n = item & 1; hq = ((item >> 1) & 3) * 2 + (wave >> 2); b = item >> 3; }
;   int kvh = hq >> 2;
;   int qrow0 = isctx ? (TL + b * 256 + n * 128) : (b * 2048 + n * 128);
;   const u16* QR = (const u16*)(p.ws + O_QR);
;   const u16* KR = (const u16*)(p.ws + O_KR);
;   const u16* VT = (const u16*)(p.ws + O_VT);
;   int ql = (wave & 3) * 32 + (lane & 31);
;   int hh = lane >> 5;
;   bf16x8 qf[4];
; #pragma unroll
;   for (int ks = 0; ks < 4; ks++) qf[ks] = *(const bf16x8*)(QR + (size_t)(qrow0 + ql) * 512 + hq * 64 + ks * 16 + hh * 8);
;   f32x16 oacc[2];
; #pragma unroll
;   for (int r = 0; r < 16; r++) { oacc[0][r] = 0.f; oacc[1][r] = 0.f; }
;   float rsum = 0.f;
;   int ntiles = isctx ? 2 : 5;
.LBB0_483:
	s_mov_b64 s[6:7], s[50:51]
	v_readlane_b32 s12, v255, 13
	v_mov_b32_e32 v8, v228
	v_mov_b64_e32 v[0:1], s[6:7]
	global_load_dwordx2 v[100:101], v[0:1], off offset:168
	global_load_dwordx2 v[0:1], v[0:1], off offset:336
	s_lshr_b32 s8, s5, 3
	s_and_b32 s16, s5, 15
	s_ashr_i32 s9, s5, 6
	s_and_b32 s8, s8, 6
	v_ashrrev_i32_e32 v2, 8, v8
	s_lshl_b32 s14, s9, 11
	s_lshl_b32 s10, s16, 7
	v_lshrrev_b32_e32 v3, 1, v8
	v_and_b32_e32 v9, 31, v8
	v_add_u32_e32 v80, s8, v2
	s_movk_i32 s8, 0x60
	s_lshl_b32 s17, s9, 8
	s_or_b32 s9, s10, s14
	v_and_or_b32 v81, v3, s8, v9
	v_or_b32_e32 v66, s9, v81
	v_ashrrev_i32_e32 v67, 31, v66
	v_lshlrev_b32_e32 v64, 6, v80
	v_lshlrev_b64 v[2:3], 10, v[66:67]
	v_bfe_u32 v10, v8, 5, 1
	v_ashrrev_i32_e32 v65, 31, v64
	v_lshlrev_b32_e32 v160, 4, v10
	s_mov_b64 s[8:9], 0x1b80c000
	v_mov_b32_e32 v7, v161
	s_mov_b64 s[10:11], 0x1ca0c000
	v_ashrrev_i32_e32 v82, 3, v8
	s_movk_i32 s20, 0x110
	s_movk_i32 s19, 0x4800
	s_mov_b32 s18, 0x9000
	v_lshlrev_b32_e32 v11, 3, v10
	v_mov_b32_e32 v86, 0
	s_and_b32 s13, s4, 15
	s_mov_b32 s15, 0
	s_add_i32 s16, s16, -1
	v_lshlrev_b32_e32 v67, 2, v10
	s_addk_i32 s17, 0x3e80
	v_mov_b32_e32 v16, 0
	v_mov_b32_e32 v17, v86
	v_mov_b32_e32 v18, v86
	v_mov_b32_e32 v19, v86
	v_mov_b32_e32 v20, v86
	v_mov_b32_e32 v21, v86
	v_mov_b32_e32 v22, v86
	v_mov_b32_e32 v23, v86
	v_mov_b32_e32 v24, v86
	v_mov_b32_e32 v25, v86
	v_mov_b32_e32 v26, v86
	v_mov_b32_e32 v27, v86
	v_mov_b32_e32 v28, v86
	v_mov_b32_e32 v29, v86
	v_mov_b32_e32 v30, v86
	v_mov_b32_e32 v31, v86
	v_mov_b32_e32 v10, v86
	v_mov_b32_e32 v12, v86
	v_mov_b32_e32 v13, v86
	v_mov_b32_e32 v14, v86
	v_mov_b32_e32 v15, v86
	v_lshl_add_u32 v104, s12, 3, v80
	v_ashrrev_i32_e32 v105, 31, v104
	s_waitcnt vmcnt(0) lgkmcnt(0)
	v_lshl_add_u64 v[100:101], v[104:105], 2, v[100:101]
	v_mov_b32_e32 v102, v0
	v_mov_b32_e32 v103, v1
	global_load_dword v106, v[100:101], off
	v_lshl_add_u64 v[2:3], v[0:1], 0, v[2:3]
	v_lshl_add_u64 v[2:3], v[64:65], 1, v[2:3]
	v_lshl_add_u64 v[2:3], v[2:3], 0, v[160:161]
	v_lshl_add_u64 v[4:5], v[2:3], 0, s[8:9]
	s_mov_b32 s8, 0x1b80c000
	v_add_co_u32_e32 v2, vcc, s8, v2
	s_movk_i32 s8, 0x90
	s_nop 0
	v_addc_co_u32_e32 v3, vcc, 0, v3, vcc
	global_load_dwordx4 v[48:51], v[4:5], off offset:32
	global_load_dwordx4 v[52:55], v[4:5], off offset:64
	global_load_dwordx4 v[56:59], v[2:3], off
	global_load_dwordx4 v[60:63], v[4:5], off offset:96
	v_lshlrev_b32_e32 v2, 4, v80
	v_and_b32_e32 v2, 0xffffffc0, v2
	v_ashrrev_i32_e32 v3, 31, v2
	v_lshl_add_u64 v[4:5], v[2:3], 1, v[0:1]
	v_lshlrev_b32_e32 v3, 4, v8
	v_and_b32_e32 v6, 0x70, v3
	v_lshl_add_u64 v[4:5], v[4:5], 0, v[6:7]
	v_lshl_add_u64 v[68:69], v[4:5], 0, s[10:11]
	v_add_u32_e32 v4, 0, v6
	v_and_b32_e32 v6, 0xf0, v3
	v_lshl_add_u64 v[0:1], v[0:1], 0, v[6:7]
	s_mov_b64 s[10:11], 0x1ce8c000
	v_lshl_add_u64 v[70:71], v[0:1], 0, s[10:11]
	v_mad_u64_u32 v[72:73], s[10:11], v82, s8, v[4:5]
	v_ashrrev_i32_e32 v5, 4, v8
	v_add_u32_e32 v0, 0, v6
	v_add_u32_e32 v6, v2, v5
	v_mul_lo_u32 v5, v5, s20
	v_add3_u32 v73, v0, v5, s19
	v_add_u32_e32 v5, 0x200, v8
	v_ashrrev_i32_e32 v83, 3, v5
	v_mad_u64_u32 v[76:77], s[10:11], v83, s8, v[4:5]
	v_ashrrev_i32_e32 v4, 4, v5
	v_add_u32_e32 v2, v2, v4
	v_add_u32_e32 v1, 0, v160
	v_mad_i64_i32 v[78:79], s[10:11], v2, s18, 0
	v_mul_lo_u32 v2, v4, s20
	v_sub_u32_e32 v3, v1, v11
	v_add3_u32 v77, v0, v2, s19
	v_mul_u32_u24_e32 v0, 0x90, v9
	v_mul_u32_u24_e32 v2, 0x110, v9
	s_mov_b32 s9, -1
	v_mad_i64_i32 v[74:75], s[10:11], v6, s18, 0
	v_add_u32_e32 v84, v1, v0
	v_add_u32_e32 v85, v3, v2
	v_mov_b32_e32 v0, 0
	v_mov_b32_e32 v1, v86
	v_mov_b32_e32 v2, v86
	v_mov_b32_e32 v3, v86
	v_mov_b32_e32 v4, v86
	v_mov_b32_e32 v5, v86
	v_mov_b32_e32 v6, v86
	v_mov_b32_e32 v7, v86
	v_mov_b32_e32 v8, v86
	v_mov_b32_e32 v9, v86
	v_mov_b32_e32 v11, v86
